# same as previous plus 8 bytes of padding after the E-phase loop so later code keeps its byte placement
# speedup vs baseline: 1.0083x; 1.0083x over previous
.LBB0_766:
	v_add_co_u32_e32 v20, vcc, 0x800000, v14
	global_load_dwordx4 v[8:11], v[14:15], off
	s_nop 0
	v_addc_co_u32_e32 v21, vcc, 0, v15, vcc
	global_load_dwordx4 v[20:23], v[20:21], off
	v_and_b32_e32 v19, 0xffc, v16
	v_and_b32_e32 v2, 0x7c000, v12
	v_lshl_add_u64 v[12:13], v[12:13], 0, s[16:17]
	v_lshl_add_u64 v[16:17], v[16:17], 0, s[24:25]
	v_add_co_u32_e32 v40, vcc, 0x1000000, v14
	s_nop 1
	v_addc_co_u32_e32 v41, vcc, 0, v15, vcc
	v_add_co_u32_e32 v42, vcc, 0x1800000, v14
	global_load_dwordx4 v[44:47], v[40:41], off
	s_nop 0
	v_addc_co_u32_e32 v43, vcc, 0, v15, vcc
	global_load_dwordx4 v[48:51], v[42:43], off
	v_lshl_add_u64 v[40:41], s[20:21], 0, v[2:3]
	v_lshlrev_b32_e32 v2, 2, v19
	v_lshl_add_u64 v[40:41], v[40:41], 0, v[2:3]
	global_load_dwordx4 v[52:55], v[40:41], off
	s_waitcnt vmcnt(0)
	v_pk_add_f32 v[26:27], v[8:9], v[20:21]
	v_pk_add_f32 v[24:25], v[10:11], v[22:23]
	v_pk_add_f32 v[8:9], v[44:45], v[48:49]
	v_pk_add_f32 v[10:11], v[46:47], v[50:51]
	v_pk_add_f32 v[22:23], v[26:27], v[8:9]
	v_pk_add_f32 v[20:21], v[24:25], v[10:11]
	v_pk_add_f32 v[8:9], v[52:53], v[22:23]
	s_nop 0
	v_fmamk_f32 v2, v8, 0x3baaaaab, v201
	v_cmp_gt_f32_e32 vcc, s91, v2
	v_mul_f32_e32 v8, 0x4f800000, v2
	v_pk_add_f32 v[10:11], v[54:55], v[20:21]
	v_cndmask_b32_e32 v2, v2, v8, vcc
	v_sqrt_f32_e32 v8, v2
	s_nop 0
	v_add_u32_e32 v19, -1, v8
	v_fma_f32 v20, -v19, v8, v2
	v_cmp_ge_f32_e64 s[42:43], 0, v20
	v_add_u32_e32 v20, 1, v8
	s_nop 0
	v_cndmask_b32_e64 v19, v8, v19, s[42:43]
	v_fma_f32 v8, -v20, v8, v2
	v_cmp_lt_f32_e64 s[42:43], 0, v8
	s_nop 1
	v_cndmask_b32_e64 v8, v19, v20, s[42:43]
	v_mul_f32_e32 v19, 0x37800000, v8
	v_cndmask_b32_e32 v8, v8, v19, vcc
	v_cmp_class_f32_e32 vcc, v2, v202
	s_nop 1
	v_cndmask_b32_e32 v2, v8, v2, vcc
	v_div_scale_f32 v8, s[4:5], v2, v2, 1.0
	v_rcp_f32_e32 v19, v8
	s_nop 0
	v_fma_f32 v20, -v8, v19, 1.0
	v_fmac_f32_e32 v19, v20, v19
	v_div_scale_f32 v20, vcc, 1.0, v2, 1.0
	v_mul_f32_e32 v21, v20, v19
	v_fma_f32 v22, -v8, v21, v20
	v_fmac_f32_e32 v21, v22, v19
	v_fma_f32 v8, -v8, v21, v20
	v_div_fmas_f32 v8, v8, v19, v21
	v_div_fixup_f32 v8, v8, v2, 1.0
	v_fmamk_f32 v2, v9, 0x3baaaaab, v201
	v_cmp_gt_f32_e32 vcc, s91, v2
	v_mul_f32_e32 v9, 0x4f800000, v2
	s_nop 0
	v_cndmask_b32_e32 v2, v2, v9, vcc
	v_sqrt_f32_e32 v9, v2
	s_nop 0
	v_add_u32_e32 v19, -1, v9
	v_fma_f32 v20, -v19, v9, v2
	v_cmp_ge_f32_e64 s[42:43], 0, v20
	v_add_u32_e32 v20, 1, v9
	s_nop 0
	v_cndmask_b32_e64 v19, v9, v19, s[42:43]
	v_fma_f32 v9, -v20, v9, v2
	v_cmp_lt_f32_e64 s[42:43], 0, v9
	s_nop 1
	v_cndmask_b32_e64 v9, v19, v20, s[42:43]
	v_mul_f32_e32 v19, 0x37800000, v9
	v_cndmask_b32_e32 v9, v9, v19, vcc
	v_cmp_class_f32_e32 vcc, v2, v202
	s_nop 1
	v_cndmask_b32_e32 v2, v9, v2, vcc
	v_div_scale_f32 v9, s[4:5], v2, v2, 1.0
	v_rcp_f32_e32 v19, v9
	s_nop 0
	v_fma_f32 v20, -v9, v19, 1.0
	v_fmac_f32_e32 v19, v20, v19
	v_div_scale_f32 v20, vcc, 1.0, v2, 1.0
	v_mul_f32_e32 v21, v20, v19
	v_fma_f32 v22, -v9, v21, v20
	v_fmac_f32_e32 v21, v22, v19
	v_fma_f32 v9, -v9, v21, v20
	v_div_fmas_f32 v9, v9, v19, v21
	v_div_fixup_f32 v9, v9, v2, 1.0
	v_fmamk_f32 v2, v10, 0x3baaaaab, v201
	v_cmp_gt_f32_e32 vcc, s91, v2
	v_mul_f32_e32 v10, 0x4f800000, v2
	s_nop 0
	v_cndmask_b32_e32 v2, v2, v10, vcc
	v_sqrt_f32_e32 v10, v2
	s_nop 0
	v_add_u32_e32 v19, -1, v10
	v_fma_f32 v20, -v19, v10, v2
	v_cmp_ge_f32_e64 s[42:43], 0, v20
	v_add_u32_e32 v20, 1, v10
	s_nop 0
	v_cndmask_b32_e64 v19, v10, v19, s[42:43]
	v_fma_f32 v10, -v20, v10, v2
	v_cmp_lt_f32_e64 s[42:43], 0, v10
	s_nop 1
	v_cndmask_b32_e64 v10, v19, v20, s[42:43]
	v_mul_f32_e32 v19, 0x37800000, v10
	v_cndmask_b32_e32 v10, v10, v19, vcc
	v_cmp_class_f32_e32 vcc, v2, v202
	s_nop 1
	v_cndmask_b32_e32 v2, v10, v2, vcc
	v_div_scale_f32 v10, s[4:5], v2, v2, 1.0
	v_rcp_f32_e32 v19, v10
	s_nop 0
	v_fma_f32 v20, -v10, v19, 1.0
	v_fmac_f32_e32 v19, v20, v19
	v_div_scale_f32 v20, vcc, 1.0, v2, 1.0
	v_mul_f32_e32 v21, v20, v19
	v_fma_f32 v22, -v10, v21, v20
	v_fmac_f32_e32 v21, v22, v19
	v_fma_f32 v10, -v10, v21, v20
	v_div_fmas_f32 v10, v10, v19, v21
	v_div_fixup_f32 v10, v10, v2, 1.0
	v_fmamk_f32 v2, v11, 0x3baaaaab, v201
	v_cmp_gt_f32_e32 vcc, s91, v2
	v_mul_f32_e32 v11, 0x4f800000, v2
	s_nop 0
	v_cndmask_b32_e32 v2, v2, v11, vcc
	v_sqrt_f32_e32 v11, v2
	s_nop 0
	v_add_u32_e32 v19, -1, v11
	v_fma_f32 v20, -v19, v11, v2
	v_cmp_ge_f32_e64 s[42:43], 0, v20
	v_add_u32_e32 v20, 1, v11
	s_nop 0
	v_cndmask_b32_e64 v19, v11, v19, s[42:43]
	v_fma_f32 v11, -v20, v11, v2
	v_cmp_lt_f32_e64 s[42:43], 0, v11
	s_nop 1
	v_cndmask_b32_e64 v11, v19, v20, s[42:43]
	v_mul_f32_e32 v19, 0x37800000, v11
	v_cndmask_b32_e32 v11, v11, v19, vcc
	v_cmp_class_f32_e32 vcc, v2, v202
	s_nop 1
	v_cndmask_b32_e32 v2, v11, v2, vcc
	v_div_scale_f32 v11, s[4:5], v2, v2, 1.0
	v_rcp_f32_e32 v19, v11
	s_mov_b64 s[4:5], 0x7ffff
	v_fma_f32 v20, -v11, v19, 1.0
	v_fmac_f32_e32 v19, v20, v19
	v_div_scale_f32 v20, vcc, 1.0, v2, 1.0
	v_mul_f32_e32 v21, v20, v19
	v_fma_f32 v22, -v11, v21, v20
	v_fmac_f32_e32 v21, v22, v19
	v_fma_f32 v11, -v11, v21, v20
	v_div_fmas_f32 v11, v11, v19, v21
	v_add_co_u32_e32 v20, vcc, 0x2bc6a000, v14
	v_div_fixup_f32 v11, v11, v2, 1.0
	s_nop 0
	v_addc_co_u32_e32 v21, vcc, 0, v15, vcc
	v_cmp_lt_u64_e32 vcc, s[4:5], v[12:13]
	v_lshl_add_u64 v[14:15], v[14:15], 0, s[22:23]
	s_or_b64 s[26:27], vcc, s[26:27]
	global_store_dwordx4 v[20:21], v[8:11], off
	s_andn2_b64 exec, exec, s[26:27]
	s_cbranch_execnz .LBB0_766
	s_nop 0
	s_nop 0
